# phase 6: GEMM A's last K-iteration prefetches GEMM B's first K-tiles; no drain/re-stage between them
# speedup vs baseline: 1.0002x; 1.0002x over previous
; template <class Epi>
; __device__ __forceinline__ void gemm_phase(LAS unsigned char* lds, const Gemm g, const StaticOrder& S, const Epi& E) {
;     ...
;     f32x4 acc[2][2][4][2];
; #pragma unroll
;     for (int a = 0; a < 2; ++a)
; #pragma unroll
;         for (int b = 0; b < 2; ++b)
; #pragma unroll
;             for (int m = 0; m < 4; ++m)
; #pragma unroll
;                 for (int n = 0; n < 2; ++n) acc[a][b][m][n] = (f32x4){0.f, 0.f, 0.f, 0.f};
;     ...
;         const bool has_next = S.next(ui + 1, nxt);
;         const char* nA = has_next ? (const char*)g.A + (size_t)nxt.pm * tstep : cA; const char* nB = has_next ? (const char*)g.Bt + (size_t)nxt.pn * tstep : cB;
;         for (int t = 0; t < nt; t += 2) {
;             const bool last = (t == nt - 2);
;             const char* a1 = cA + (size_t)(t + 1) * kstep;
;             const char* a2 = last ? nA : cA + (size_t)(t + 2) * kstep; const char* b2 = last ? nB : cB + (size_t)(t + 2) * kstep;
.LBB0_913:
	s_ashr_i32 s19, s18, 31
	v_cmp_lt_i64_e32 vcc, s[22:23], v[152:153]
	s_lshl_b64 s[22:23], s[18:19], 19
	s_add_u32 s22, s42, s22
	s_addc_u32 s23, s43, s23
	s_add_u32 s98, s28, 0xfc42000
	s_addc_u32 s99, s29, 0
	s_add_u32 s100, s30, 0x400000
	s_addc_u32 s101, s31, 0
	s_and_b64 s[24:25], vcc, exec
	s_cselect_b32 s19, s23, s99
	s_cselect_b32 s63, s22, s98
	s_ashr_i32 s21, s20, 31
	s_lshl_b64 s[24:25], s[20:21], 19
	s_add_u32 s24, s44, s24
	s_addc_u32 s25, s48, s25
	s_and_b64 s[34:35], vcc, exec
	s_cselect_b32 s21, s25, s101
	s_cselect_b32 s64, s24, s100
	s_add_u32 s28, s28, 0x40080
	s_addc_u32 s29, s29, 0
	s_add_u32 s65, s30, 0x100
	v_mov_b32_e32 v0, 0
	s_addc_u32 s66, s31, 0
	s_mov_b32 s67, -2
	v_mov_b32_e32 v1, v0
	v_mov_b32_e32 v2, v0
	v_mov_b32_e32 v3, v0
	v_mov_b32_e32 v4, v0
	v_mov_b32_e32 v5, v0
	v_mov_b32_e32 v6, v0
	v_mov_b32_e32 v7, v0
	s_waitcnt vmcnt(0)
	v_mov_b32_e32 v16, v0
	v_mov_b32_e32 v17, v0
	v_mov_b32_e32 v18, v0
	v_mov_b32_e32 v19, v0
	v_mov_b32_e32 v20, v0
	v_mov_b32_e32 v21, v0
	v_mov_b32_e32 v22, v0
	v_mov_b32_e32 v23, v0
	v_mov_b32_e32 v32, v0
	v_mov_b32_e32 v33, v0
	v_mov_b32_e32 v34, v0
	v_mov_b32_e32 v35, v0
	v_mov_b32_e32 v36, v0
	v_mov_b32_e32 v37, v0
	v_mov_b32_e32 v38, v0
	v_mov_b32_e32 v39, v0
	v_mov_b32_e32 v48, v0
	v_mov_b32_e32 v49, v0
	v_mov_b32_e32 v50, v0
	v_mov_b32_e32 v51, v0
	v_mov_b32_e32 v52, v0
	v_mov_b32_e32 v53, v0
	v_mov_b32_e32 v54, v0
	v_mov_b32_e32 v55, v0
	v_mov_b32_e32 v8, v0
	v_mov_b32_e32 v9, v0
	v_mov_b32_e32 v10, v0
	v_mov_b32_e32 v11, v0
	v_mov_b32_e32 v12, v0
	v_mov_b32_e32 v13, v0
	v_mov_b32_e32 v14, v0
	v_mov_b32_e32 v15, v0
	v_mov_b32_e32 v24, v0
	v_mov_b32_e32 v25, v0
	v_mov_b32_e32 v26, v0
	v_mov_b32_e32 v27, v0
	v_mov_b32_e32 v28, v0
	v_mov_b32_e32 v29, v0
	v_mov_b32_e32 v30, v0
	v_mov_b32_e32 v31, v0
	v_mov_b32_e32 v40, v0
	v_mov_b32_e32 v41, v0
	v_mov_b32_e32 v42, v0
	v_mov_b32_e32 v43, v0
	v_mov_b32_e32 v44, v0
	v_mov_b32_e32 v45, v0
	v_mov_b32_e32 v46, v0
	v_mov_b32_e32 v47, v0
	v_mov_b32_e32 v56, v0
	v_mov_b32_e32 v57, v0
	v_mov_b32_e32 v58, v0
	v_mov_b32_e32 v59, v0
	v_mov_b32_e32 v60, v0
	v_mov_b32_e32 v61, v0
	v_mov_b32_e32 v62, v0
	v_mov_b32_e32 v63, v0
	v_mov_b32_e32 v64, v0
	v_mov_b32_e32 v65, v0
	v_mov_b32_e32 v66, v0
	v_mov_b32_e32 v67, v0
	v_mov_b32_e32 v68, v0
	v_mov_b32_e32 v69, v0
	v_mov_b32_e32 v70, v0
	v_mov_b32_e32 v71, v0
	v_mov_b32_e32 v80, v0
	v_mov_b32_e32 v81, v0
	v_mov_b32_e32 v82, v0
	v_mov_b32_e32 v83, v0
	v_mov_b32_e32 v84, v0
	v_mov_b32_e32 v85, v0
	v_mov_b32_e32 v86, v0
	v_mov_b32_e32 v87, v0
	v_mov_b32_e32 v96, v0
	v_mov_b32_e32 v97, v0
	v_mov_b32_e32 v98, v0
	v_mov_b32_e32 v99, v0
	v_mov_b32_e32 v100, v0
	v_mov_b32_e32 v101, v0
	v_mov_b32_e32 v102, v0
	v_mov_b32_e32 v103, v0
	v_mov_b32_e32 v112, v0
	v_mov_b32_e32 v113, v0
	v_mov_b32_e32 v114, v0
	v_mov_b32_e32 v115, v0
	v_mov_b32_e32 v116, v0
	v_mov_b32_e32 v117, v0
	v_mov_b32_e32 v118, v0
	v_mov_b32_e32 v119, v0
	v_mov_b32_e32 v72, v0
	v_mov_b32_e32 v73, v0
	v_mov_b32_e32 v74, v0
	v_mov_b32_e32 v75, v0
	v_mov_b32_e32 v76, v0
	v_mov_b32_e32 v77, v0
	v_mov_b32_e32 v78, v0
	v_mov_b32_e32 v79, v0
	v_mov_b32_e32 v88, v0
	v_mov_b32_e32 v89, v0
	v_mov_b32_e32 v90, v0
	v_mov_b32_e32 v91, v0
	v_mov_b32_e32 v92, v0
	v_mov_b32_e32 v93, v0
	v_mov_b32_e32 v94, v0
	v_mov_b32_e32 v95, v0
	v_mov_b32_e32 v104, v0
	v_mov_b32_e32 v105, v0
	v_mov_b32_e32 v106, v0
	v_mov_b32_e32 v107, v0
	v_mov_b32_e32 v108, v0
	v_mov_b32_e32 v109, v0
	v_mov_b32_e32 v110, v0
	v_mov_b32_e32 v111, v0
	v_mov_b32_e32 v120, v0
	v_mov_b32_e32 v121, v0
	v_mov_b32_e32 v122, v0
	v_mov_b32_e32 v123, v0
	v_mov_b32_e32 v124, v0
	v_mov_b32_e32 v125, v0
	v_mov_b32_e32 v126, v0
	v_mov_b32_e32 v127, v0

; #define PG8_STAGE(bufoff, gbase, voff) do { _Pragma("unroll") for (int _i = 0; _i < 2; ++_i) \
;         __builtin_amdgcn_global_load_lds((const unsigned*)((const char*)(gbase) + (voff)[_i]), (LAS unsigned*)(lds + (bufoff) + ldsw + _i * 8192), 16, 0, 0); } while (0)
; #define PG8_WAIT_V(n) asm volatile("s_waitcnt vmcnt(" #n ")" ::: "memory")
; #define PG8_BAR __builtin_amdgcn_s_barrier()
; template <class Epi>
; __device__ __forceinline__ void gemm_phase(LAS unsigned char* lds, const Gemm g, const StaticOrder& S, const Epi& E) {
;     const int tid = threadIdx.x, wid = __builtin_amdgcn_readfirstlane(tid >> 6), lane = tid & 63, wr = wid >> 2, wc = wid & 3, fr = lane & 15, fq = lane >> 4;
;     const int K = g.K, nt = K / BK;
;     unsigned voffA[2], voffB[2];
; #pragma unroll
;     for (int i = 0; i < 2; ++i) { int R, C; stage_rc(tid * 16 + i * 8192, R, C); const int Rb = Epi::PERM ? ((R & ~31) + perm32(R & 31)) : R;
;         voffA[i] = (unsigned)(R * K + C) * 2u; voffB[i] = (unsigned)(Rb * K + C) * 2u; }
;     const size_t kstep = (size_t)(BK * 2);
;     const size_t hstep = (size_t)HALF * K * 2;
;     const size_t tstep = 2 * hstep;
;     const unsigned ldsw = (unsigned)wid * 1024u;
;     const int aoff = lds_byte(wr * 64 + fr, fq * 8), boff = lds_byte(wc * 32 + fr, fq * 8);
;     ...
;     Unit cur, nxt; int ui = 0;
;     if (!S.next(0, cur)) return;
;     f32x4 acc[2][2][4][2];
; #pragma unroll
;     for (int a = 0; a < 2; ++a)
; #pragma unroll
;         for (int b = 0; b < 2; ++b)
; #pragma unroll
;             for (int m = 0; m < 4; ++m)
; #pragma unroll
;                 for (int n = 0; n < 2; ++n) acc[a][b][m][n] = (f32x4){0.f, 0.f, 0.f, 0.f};
;     bf16x8 At[4][2], B0[2][2], B1[2][2];
;     const char* cA = (const char*)g.A + (size_t)cur.pm * tstep; const char* cB = (const char*)g.Bt + (size_t)cur.pn * tstep;
;     PG8_STAGE(PG8_SB(0, 0), cB, voffB); PG8_STAGE(PG8_SA(0, 0), cA, voffA); PG8_STAGE(PG8_SB(0, 1), cB + hstep, voffB); PG8_STAGE(PG8_SA(0, 1), cA + hstep, voffA);
;     if (wr == 1) PG8_BAR;
;     PG8_WAIT_V(4); PG8_BAR;
;     PG8_STAGE(PG8_SB(1, 0), cB + kstep, voffB); PG8_STAGE(PG8_SA(1, 0), cA + kstep, voffA); PG8_STAGE(PG8_SB(1, 1), cB + hstep + kstep, voffB);
;     PG8_WAIT_V(6); PG8_BAR;
;     ...
;     PG8_WAIT_V(0);
;     if (wr == 0) PG8_BAR;
;     PG8_BAR;
.LBB0_919:
	s_andn2_b64 vcc, exec, s[6:7]
	v_readfirstlane_b32 s34, v214
	s_cbranch_vccnz .LBB0_936
	s_lshr_b32 s6, s34, 6
	s_lshr_b32 s3, s34, 8
	s_lshl_b32 s35, s6, 10
	s_add_u32 s41, s12, 0x12dc2000
	s_addc_u32 s42, s13, 0
	s_add_u32 s43, s12, 0xdfc2000
	s_addc_u32 s44, s13, 0
	s_and_b64 s[8:9], s[8:9], exec
	s_cselect_b32 s2, s47, s46
	s_add_i32 s2, s2, s45
	s_sext_i32_i16 s7, s2
	s_bfe_u32 s7, s7, 0x60019
	s_add_i32 s7, s2, s7
	s_sext_i32_i16 s8, s7
	s_and_b32 s7, s7, 0xffc0
	s_sub_i32 s7, s2, s7
	s_bfe_i32 s2, s7, 0x80000
	s_bfe_u32 s2, s2, 0x3000c
	s_add_i32 s9, s7, s2
	s_bfe_i32 s2, s9, 0x80000
	s_and_b32 s9, s9, 0xf8
	s_ashr_i32 s8, s8, 6
	s_sub_i32 s7, s7, s9
	s_lshl_b32 s8, s8, 3
	s_sext_i32_i16 s2, s2
	s_sext_i32_i8 s7, s7
	s_lshr_b32 s2, s2, 3
	s_add_i32 s24, s8, s7
	s_ashr_i32 s25, s24, 31
	s_bfe_i64 s[10:11], s[2:3], 0x100000
	s_lshl_b64 s[8:9], s[24:25], 19
	s_lshl_b64 s[10:11], s[10:11], 19
	s_add_u32 s28, s43, s10
	s_addc_u32 s29, s44, s11
	s_add_i32 s25, s35, 0
	s_add_i32 m0, s25, 0x10000
	v_lshl_add_u64 v[0:1], s[28:29], 0, v[174:175]
	s_nop 0
	s_add_i32 m0, s25, 0x12000
	s_add_u32 s26, s41, s8
	v_lshl_add_u64 v[2:3], s[28:29], 0, v[178:179]
	s_addc_u32 s27, s42, s9
	s_add_i32 s45, s25, 0x2000
	s_nop 0
	v_lshl_add_u64 v[6:7], s[26:27], 0, v[172:173]
	s_mov_b32 m0, s25
	s_add_u32 s8, s28, 0x40000
	s_nop 0
	v_lshl_add_u64 v[4:5], s[26:27], 0, v[176:177]
	s_mov_b32 m0, s45
	s_addc_u32 s9, s29, 0
	s_nop 0
	s_add_i32 m0, s25, 0x14000
	v_lshl_add_u64 v[8:9], s[8:9], 0, v[174:175]
	s_nop 0
	s_add_i32 m0, s25, 0x16000
	v_lshl_add_u64 v[8:9], s[8:9], 0, v[178:179]
	s_add_u32 s8, s26, 0x40000
	s_addc_u32 s9, s27, 0
	s_add_i32 s46, s25, 0x4000
	s_nop 0
	v_lshl_add_u64 v[8:9], s[8:9], 0, v[172:173]
	s_mov_b32 m0, s46
	s_add_i32 s47, s25, 0x6000
	s_nop 0
	v_lshl_add_u64 v[8:9], s[8:9], 0, v[176:177]
	s_mov_b32 m0, s47
	s_cmp_lg_u32 s3, 1
	s_nop 0
	s_mov_b32 s48, 0
	s_cbranch_scc1 .LBB0_922
	s_nop 0
.LBB0_922:
	s_lshl_b32 s6, s6, 5
	s_lshl_b32 s16, s3, 13
	s_and_b32 s17, s6, 0x60
	s_add_u32 s6, s12, 0x18042000
	s_mov_b64 s[8:9], 0x80
	s_addc_u32 s7, s13, 0
	s_add_i32 m0, s25, 0x18000
	v_lshl_add_u64 v[0:1], v[0:1], 0, s[8:9]
	s_nop 0
	s_nop 0
	s_nop 0
	v_lshl_add_u64 v[0:1], v[2:3], 0, s[8:9]
	s_add_i32 m0, s25, 0x1a000
	s_add_i32 s49, s25, 0x8000
	s_add_i32 s50, s25, 0xa000
	s_nop 0
	v_lshl_add_u64 v[0:1], v[6:7], 0, s[8:9]
	s_mov_b32 m0, s49
	s_add_u32 s10, s28, 0x40080
	s_nop 0
	v_lshl_add_u64 v[0:1], v[4:5], 0, s[8:9]
	s_mov_b32 m0, s50
	s_addc_u32 s11, s29, 0
	s_nop 0
	s_add_i32 m0, s25, 0x1c000
	v_lshl_add_u64 v[0:1], s[10:11], 0, v[174:175]
	s_nop 0
	v_lshl_add_u64 v[0:1], s[10:11], 0, v[178:179]
	s_add_i32 m0, s25, 0x1e000
	v_lshlrev_b32_e32 v203, 2, v202
	s_nop 0
	v_lshl_or_b32 v0, v202, 6, v181
	v_and_b32_e32 v1, 32, v203
	v_bitop3_b32 v0, v0, s16, v1 bitop3:0xde
	v_lshlrev_b32_e32 v1, 8, v214
	v_and_b32_e32 v1, 0x38000, v1
	v_lshlrev_b32_e32 v2, 11, v170
	v_or3_b32 v1, v168, v1, v2
	v_or_b32_e32 v206, s17, v180
	v_add_u32_e32 v180, v1, v169
	v_lshlrev_b32_e32 v1, 4, v171
	s_nop 0
	v_and_b32_e32 v1, 0x78000, v1
	v_lshl_or_b32 v205, s17, 7, v182
	v_mov_b32_e32 v181, 0
	v_or3_b32 v1, v168, v1, v2
	s_add_i32 s51, 0, 0x10000
	s_add_i32 s54, 0, 0x14000
	s_sext_i32_i8 s57, s2
	v_lshl_or_b32 v204, s3, 6, v202
	v_add_u32_e32 v182, v1, v169
	v_mov_b32_e32 v183, v181
	v_mov_b64_e32 v[184:185], 0x100
	v_mov_b64_e32 v[186:187], 0xff
	v_add_u32_e32 v207, s51, v205
	v_add_u32_e32 v208, 0, v0
	v_add_u32_e32 v209, s54, v205
	s_movk_i32 s55, 0x4800
	s_mov_b64 s[10:11], 0x3800
	s_movk_i32 s56, 0x3000
	s_nop 0

; template <class Epi>
; __device__ __forceinline__ void gemm_phase(LAS unsigned char* lds, const Gemm g, const StaticOrder& S, const Epi& E) {
;     ...
;         const bool has_next = S.next(ui + 1, nxt);
;         const char* nA = has_next ? (const char*)g.A + (size_t)nxt.pm * tstep : cA; const char* nB = has_next ? (const char*)g.Bt + (size_t)nxt.pn * tstep : cB;
;         for (int t = 0; t < nt; t += 2) {
;             const bool last = (t == nt - 2);
;             const char* a1 = cA + (size_t)(t + 1) * kstep;
;             const char* a2 = last ? nA : cA + (size_t)(t + 2) * kstep; const char* b2 = last ? nB : cB + (size_t)(t + 2) * kstep;
;             const char* a3 = a2 + kstep; const char* b3 = b2 + kstep;
;     ...
; #pragma unroll
;         for (int a = 0; a < 2; ++a)
; #pragma unroll
;             for (int b = 0; b < 2; ++b)
; #pragma unroll
;                 for (int m = 0; m < 4; ++m)
; #pragma unroll
;                     for (int n = 0; n < 2; ++n) acc[a][b][m][n] = (f32x4){0.f, 0.f, 0.f, 0.f};
;         cur = nxt; cA = nA; cB = nB; ++ui;
.LBB0_929:
	s_ashr_i32 s17, s16, 31
	v_cmp_lt_i64_e32 vcc, s[20:21], v[184:185]
	s_lshl_b64 s[20:21], s[16:17], 19
	s_add_u32 s20, s41, s20
	s_addc_u32 s21, s42, s21
	s_and_b64 s[22:23], vcc, exec
	s_cselect_b32 s17, s21, s27
	s_cselect_b32 s58, s20, s26
	s_ashr_i32 s19, s18, 31
	s_lshl_b64 s[22:23], s[18:19], 19
	s_add_u32 s22, s43, s22
	s_addc_u32 s23, s44, s23
	s_and_b64 s[30:31], vcc, exec
	s_cselect_b32 s19, s23, s29
	s_cselect_b32 s59, s22, s28
	s_add_u32 s26, s26, 0x40080
	s_addc_u32 s27, s27, 0
	s_add_u32 s60, s28, 0x100
	v_mov_b32_e32 v0, 0
	s_addc_u32 s61, s29, 0
	s_mov_b32 s62, -2
	v_mov_b32_e32 v1, v0
	v_mov_b32_e32 v2, v0
	v_mov_b32_e32 v3, v0
	v_mov_b32_e32 v4, v0
	v_mov_b32_e32 v5, v0
	v_mov_b32_e32 v6, v0
	v_mov_b32_e32 v7, v0
	s_nop 0
	v_mov_b32_e32 v16, v0
	v_mov_b32_e32 v17, v0
	v_mov_b32_e32 v18, v0
	v_mov_b32_e32 v19, v0
	v_mov_b32_e32 v20, v0
	v_mov_b32_e32 v21, v0
	v_mov_b32_e32 v22, v0
	v_mov_b32_e32 v23, v0
	v_mov_b32_e32 v32, v0
	v_mov_b32_e32 v33, v0
	v_mov_b32_e32 v34, v0
	v_mov_b32_e32 v35, v0
	v_mov_b32_e32 v36, v0
	v_mov_b32_e32 v37, v0
	v_mov_b32_e32 v38, v0
	v_mov_b32_e32 v39, v0
	v_mov_b32_e32 v48, v0
	v_mov_b32_e32 v49, v0
	v_mov_b32_e32 v50, v0
	v_mov_b32_e32 v51, v0
	v_mov_b32_e32 v52, v0
	v_mov_b32_e32 v53, v0
	v_mov_b32_e32 v54, v0
	v_mov_b32_e32 v55, v0
	v_mov_b32_e32 v8, v0
	v_mov_b32_e32 v9, v0
	v_mov_b32_e32 v10, v0
	v_mov_b32_e32 v11, v0
	v_mov_b32_e32 v12, v0
	v_mov_b32_e32 v13, v0
	v_mov_b32_e32 v14, v0
	v_mov_b32_e32 v15, v0
	v_mov_b32_e32 v24, v0
	v_mov_b32_e32 v25, v0
	v_mov_b32_e32 v26, v0
	v_mov_b32_e32 v27, v0
	v_mov_b32_e32 v28, v0
	v_mov_b32_e32 v29, v0
	v_mov_b32_e32 v30, v0
	v_mov_b32_e32 v31, v0
	v_mov_b32_e32 v40, v0
	v_mov_b32_e32 v41, v0
	v_mov_b32_e32 v42, v0
	v_mov_b32_e32 v43, v0
	v_mov_b32_e32 v44, v0
	v_mov_b32_e32 v45, v0
	v_mov_b32_e32 v46, v0
	v_mov_b32_e32 v47, v0
	v_mov_b32_e32 v56, v0
	v_mov_b32_e32 v57, v0
	v_mov_b32_e32 v58, v0
	v_mov_b32_e32 v59, v0
	v_mov_b32_e32 v60, v0
	v_mov_b32_e32 v61, v0
	v_mov_b32_e32 v62, v0
	v_mov_b32_e32 v63, v0
	v_mov_b32_e32 v64, v0
	v_mov_b32_e32 v65, v0
	v_mov_b32_e32 v66, v0
	v_mov_b32_e32 v67, v0
	v_mov_b32_e32 v68, v0
	v_mov_b32_e32 v69, v0
	v_mov_b32_e32 v70, v0
	v_mov_b32_e32 v71, v0
	v_mov_b32_e32 v80, v0
	v_mov_b32_e32 v81, v0
	v_mov_b32_e32 v82, v0
	v_mov_b32_e32 v83, v0
	v_mov_b32_e32 v84, v0
	v_mov_b32_e32 v85, v0
	v_mov_b32_e32 v86, v0
	v_mov_b32_e32 v87, v0
	v_mov_b32_e32 v96, v0
	v_mov_b32_e32 v97, v0
	v_mov_b32_e32 v98, v0
	v_mov_b32_e32 v99, v0
	v_mov_b32_e32 v100, v0
	v_mov_b32_e32 v101, v0
	v_mov_b32_e32 v102, v0
	v_mov_b32_e32 v103, v0
	v_mov_b32_e32 v112, v0
	v_mov_b32_e32 v113, v0
	v_mov_b32_e32 v114, v0
	v_mov_b32_e32 v115, v0
	v_mov_b32_e32 v116, v0
	v_mov_b32_e32 v117, v0
	v_mov_b32_e32 v118, v0
	v_mov_b32_e32 v119, v0
	v_mov_b32_e32 v72, v0
	v_mov_b32_e32 v73, v0
	v_mov_b32_e32 v74, v0
	v_mov_b32_e32 v75, v0
	v_mov_b32_e32 v76, v0
	v_mov_b32_e32 v77, v0
	v_mov_b32_e32 v78, v0
	v_mov_b32_e32 v79, v0
	v_mov_b32_e32 v88, v0
	v_mov_b32_e32 v89, v0
	v_mov_b32_e32 v90, v0
	v_mov_b32_e32 v91, v0
	v_mov_b32_e32 v92, v0
	v_mov_b32_e32 v93, v0
	v_mov_b32_e32 v94, v0
	v_mov_b32_e32 v95, v0
	v_mov_b32_e32 v104, v0
	v_mov_b32_e32 v105, v0
	v_mov_b32_e32 v106, v0
	v_mov_b32_e32 v107, v0
	v_mov_b32_e32 v108, v0
	v_mov_b32_e32 v109, v0
	v_mov_b32_e32 v110, v0
	v_mov_b32_e32 v111, v0
	v_mov_b32_e32 v120, v0
	v_mov_b32_e32 v121, v0
	v_mov_b32_e32 v122, v0
	v_mov_b32_e32 v123, v0
	v_mov_b32_e32 v124, v0
	v_mov_b32_e32 v125, v0
	v_mov_b32_e32 v126, v0
	v_mov_b32_e32 v127, v0

; __global__ void __launch_bounds__(512, 2) fwd(Params P) {
;     extern __shared__ __attribute__((aligned(16))) unsigned char shm[];
	.amdhsa_kernel _Z3fwd6Params
		.amdhsa_group_segment_fixed_size 0
		.amdhsa_private_segment_fixed_size 0
		.amdhsa_kernarg_size 528
		.amdhsa_user_sgpr_count 2
		.amdhsa_user_sgpr_dispatch_ptr 0
		.amdhsa_user_sgpr_queue_ptr 0
		.amdhsa_user_sgpr_kernarg_segment_ptr 1
		.amdhsa_user_sgpr_dispatch_id 0
		.amdhsa_user_sgpr_kernarg_preload_length 0
		.amdhsa_user_sgpr_kernarg_preload_offset 0
		.amdhsa_user_sgpr_private_segment_size 0
		.amdhsa_uses_dynamic_stack 0
		.amdhsa_enable_private_segment 0
		.amdhsa_system_sgpr_workgroup_id_x 1
		.amdhsa_system_sgpr_workgroup_id_y 0
		.amdhsa_system_sgpr_workgroup_id_z 0
		.amdhsa_system_sgpr_workgroup_info 0
		.amdhsa_system_vgpr_workitem_id 2
		.amdhsa_next_free_vgpr 246
		.amdhsa_next_free_sgpr 102
		.amdhsa_accum_offset 248
		.amdhsa_reserve_vcc 1
		.amdhsa_float_round_mode_32 0
		.amdhsa_float_round_mode_16_64 0
		.amdhsa_float_denorm_mode_32 3
		.amdhsa_float_denorm_mode_16_64 3
		.amdhsa_dx10_clamp 1
		.amdhsa_ieee_mode 1
		.amdhsa_fp16_overflow 0
		.amdhsa_tg_split 0
		.amdhsa_exception_fp_ieee_invalid_op 0
		.amdhsa_exception_fp_denorm_src 0
		.amdhsa_exception_fp_ieee_div_zero 0
		.amdhsa_exception_fp_ieee_overflow 0
		.amdhsa_exception_fp_ieee_underflow 0
		.amdhsa_exception_fp_ieee_inexact 0
		.amdhsa_exception_int_div_zero 0
	.end_amdhsa_kernel

; __global__ void __launch_bounds__(512, 2) fwd(Params P) {
;     extern __shared__ __attribute__((aligned(16))) unsigned char shm[];
amdhsa.kernels:
  - .agpr_count:     0
    .args:
      - .offset:         0
        .size:           272
        .value_kind:     by_value
      - .offset:         272
        .size:           4
        .value_kind:     hidden_block_count_x
      - .offset:         276
        .size:           4
        .value_kind:     hidden_block_count_y
      - .offset:         280
        .size:           4
        .value_kind:     hidden_block_count_z
      - .offset:         284
        .size:           2
        .value_kind:     hidden_group_size_x
      - .offset:         286
        .size:           2
        .value_kind:     hidden_group_size_y
      - .offset:         288
        .size:           2
        .value_kind:     hidden_group_size_z
      - .offset:         290
        .size:           2
        .value_kind:     hidden_remainder_x
      - .offset:         292
        .size:           2
        .value_kind:     hidden_remainder_y
      - .offset:         294
        .size:           2
        .value_kind:     hidden_remainder_z
      - .offset:         312
        .size:           8
        .value_kind:     hidden_global_offset_x
      - .offset:         320
        .size:           8
        .value_kind:     hidden_global_offset_y
      - .offset:         328
        .size:           8
        .value_kind:     hidden_global_offset_z
      - .offset:         336
        .size:           2
        .value_kind:     hidden_grid_dims
      - .offset:         360
        .size:           8
        .value_kind:     hidden_multigrid_sync_arg
      - .offset:         392
        .size:           4
        .value_kind:     hidden_dynamic_lds_size
    .group_segment_fixed_size: 0
    .kernarg_segment_align: 8
    .kernarg_segment_size: 528
    .language:       OpenCL C
    .language_version:
      - 2
      - 0
    .max_flat_workgroup_size: 512
    .name:           _Z3fwd6Params
    .private_segment_fixed_size: 0
    .sgpr_count:     108
    .sgpr_spill_count: 112
    .symbol:         _Z3fwd6Params.kd
    .uniform_work_group_size: 1
    .uses_dynamic_stack: false
    .vgpr_count:     246
    .vgpr_spill_count: 0
    .wavefront_size: 64
